# grid barrier: non-leader workgroups poll the cross-XCD release word directly (one relay hop less)
# baseline (speedup 1.0000x reference)
; __device__ __forceinline__ unsigned xb_ld(unsigned* p)              { return __hip_atomic_load(p, __ATOMIC_RELAXED, __HIP_MEMORY_SCOPE_AGENT); }
; __device__ __forceinline__ unsigned xb_add(unsigned* p, unsigned v) { return __hip_atomic_fetch_add(p, v, __ATOMIC_RELAXED, __HIP_MEMORY_SCOPE_AGENT); }
; #define XB_SPIN(cond, bar) do { unsigned _sp = 0; while (cond) { __builtin_amdgcn_s_sleep(1); \
;     if ((++_sp & 255u) == 0u) { if (xb_ld(&(bar)[XB_TMO])) break; if (_sp > XB_SPIN_CAP) { atomicAdd(&(bar)[XB_TMO], 1u); break; } } } } while (0)
; __device__ __forceinline__ void xcd_barrier(const XcdBarrier& b) {
;     ...
;         const unsigned old = xb_add(&bar[XB_XSUB(b.x)], 1u);
;         const unsigned gen = old / nloc;
;         if (old + 1u == (gen + 1u) * nloc) {
;             __builtin_amdgcn_fence(__ATOMIC_RELEASE, "agent");
;             asm volatile("s_waitcnt vmcnt(0)" ::: "memory");
;             const unsigned og = xb_add(&bar[XB_TOP], 1u);
;             const unsigned tg = og / nx;
;             if (og + 1u == (tg + 1u) * nx) xb_add(&bar[XB_TOPGEN], 1u);
;             else XB_SPIN(xb_ld(&bar[XB_TOPGEN]) == tg, bar);
;             __builtin_amdgcn_fence(__ATOMIC_ACQUIRE, "agent");
;             xb_add(&bar[XB_XGEN(b.x)], 1u);
;             asm volatile("s_waitcnt vmcnt(0)" ::: "memory");
;         } else {
;             XB_SPIN(xb_ld(&bar[XB_XGEN(b.x)]) == gen, bar);
.LBB0_108:
	s_or_b64 exec, exec, s[4:5]
	v_cvt_f32_u32_e32 v8, v6
	s_waitcnt vmcnt(0)
	v_readfirstlane_b32 s4, v7
	v_sub_u32_e32 v7, 0, v6
	v_rcp_iflag_f32_e32 v8, v8
	v_add_u32_e32 v9, s4, v5
	v_mul_f32_e32 v8, 0x4f7ffffe, v8
	v_cvt_u32_f32_e32 v8, v8
	v_mul_lo_u32 v5, v7, v8
	v_mul_hi_u32 v5, v8, v5
	v_add_u32_e32 v5, v8, v5
	v_mul_hi_u32 v5, v9, v5
	v_mul_lo_u32 v7, v5, v6
	v_sub_u32_e32 v7, v9, v7
	v_add_u32_e32 v8, 1, v5
	v_sub_u32_e32 v10, v7, v6
	v_cmp_ge_u32_e32 vcc, v7, v6
	s_nop 1
	v_cndmask_b32_e32 v5, v5, v8, vcc
	v_cndmask_b32_e32 v7, v7, v10, vcc
	v_add_u32_e32 v8, 1, v5
	v_cmp_ge_u32_e32 vcc, v7, v6
	v_add_u32_e32 v7, 1, v9
	s_nop 0
	v_cndmask_b32_e32 v5, v5, v8, vcc
	v_mul_lo_u32 v8, v6, v5
	v_add_u32_e32 v6, v8, v6
	v_cmp_ne_u32_e32 vcc, v7, v6
	s_and_saveexec_b64 s[4:5], vcc
	s_xor_b64 s[4:5], exec, s[4:5]
	s_cbranch_execz .LBB0_122
	v_readlane_b32 s24, v249, 49
	v_readlane_b32 s25, v249, 50
	s_waitcnt lgkmcnt(0)
	s_nop 3
	global_load_dword v4, v137, s[24:25] sc1
	s_waitcnt vmcnt(0)
	v_cmp_eq_u32_e32 vcc, v4, v5
	s_and_saveexec_b64 s[24:25], vcc
	s_cbranch_execz .LBB0_121
	s_mov_b32 s28, 1
	s_mov_b64 s[26:27], 0
	s_branch .LBB0_112

; __device__ __forceinline__ unsigned xb_ld(unsigned* p)              { return __hip_atomic_load(p, __ATOMIC_RELAXED, __HIP_MEMORY_SCOPE_AGENT); }
; #define XB_SPIN(cond, bar) do { unsigned _sp = 0; while (cond) { __builtin_amdgcn_s_sleep(1); \
;     if ((++_sp & 255u) == 0u) { if (xb_ld(&(bar)[XB_TMO])) break; if (_sp > XB_SPIN_CAP) { atomicAdd(&(bar)[XB_TMO], 1u); break; } } } } while (0)
; __device__ __forceinline__ void xcd_barrier(const XcdBarrier& b) {
;     ...
;             XB_SPIN(xb_ld(&bar[XB_XGEN(b.x)]) == gen, bar);
.LBB0_114:
	v_readlane_b32 s38, v249, 49
	v_readlane_b32 s39, v249, 50
	s_add_i32 s28, s28, 1
	s_mov_b64 s[44:45], -1
	s_nop 2
	global_load_dword v4, v137, s[38:39] sc1
	s_waitcnt vmcnt(0)
	v_cmp_ne_u32_e32 vcc, v4, v5
	s_orn2_b64 s[42:43], vcc, exec
	s_branch .LBB0_111

; __device__ __forceinline__ unsigned xb_ld(unsigned* p)              { return __hip_atomic_load(p, __ATOMIC_RELAXED, __HIP_MEMORY_SCOPE_AGENT); }
; __device__ __forceinline__ unsigned xb_add(unsigned* p, unsigned v) { return __hip_atomic_fetch_add(p, v, __ATOMIC_RELAXED, __HIP_MEMORY_SCOPE_AGENT); }
; #define XB_SPIN(cond, bar) do { unsigned _sp = 0; while (cond) { __builtin_amdgcn_s_sleep(1); \
;     if ((++_sp & 255u) == 0u) { if (xb_ld(&(bar)[XB_TMO])) break; if (_sp > XB_SPIN_CAP) { atomicAdd(&(bar)[XB_TMO], 1u); break; } } } } while (0)
; __device__ __forceinline__ void xcd_barrier(const XcdBarrier& b) {
;     ...
;         const unsigned old = xb_add(&bar[XB_XSUB(b.x)], 1u);
;         const unsigned gen = old / nloc;
;         if (old + 1u == (gen + 1u) * nloc) {
;             __builtin_amdgcn_fence(__ATOMIC_RELEASE, "agent");
;             asm volatile("s_waitcnt vmcnt(0)" ::: "memory");
;             const unsigned og = xb_add(&bar[XB_TOP], 1u);
;             const unsigned tg = og / nx;
;             if (og + 1u == (tg + 1u) * nx) xb_add(&bar[XB_TOPGEN], 1u);
;             else XB_SPIN(xb_ld(&bar[XB_TOPGEN]) == tg, bar);
;             __builtin_amdgcn_fence(__ATOMIC_ACQUIRE, "agent");
;             xb_add(&bar[XB_XGEN(b.x)], 1u);
;             asm volatile("s_waitcnt vmcnt(0)" ::: "memory");
;         } else {
;             XB_SPIN(xb_ld(&bar[XB_XGEN(b.x)]) == gen, bar);
.LBB0_253:
	s_or_b64 exec, exec, s[4:5]
	v_cvt_f32_u32_e32 v8, v6
	s_waitcnt vmcnt(0)
	v_readfirstlane_b32 s4, v7
	v_sub_u32_e32 v7, 0, v6
	v_rcp_iflag_f32_e32 v8, v8
	v_add_u32_e32 v9, s4, v5
	v_mul_f32_e32 v8, 0x4f7ffffe, v8
	v_cvt_u32_f32_e32 v8, v8
	v_mul_lo_u32 v5, v7, v8
	v_mul_hi_u32 v5, v8, v5
	v_add_u32_e32 v5, v8, v5
	v_mul_hi_u32 v5, v9, v5
	v_mul_lo_u32 v7, v5, v6
	v_sub_u32_e32 v7, v9, v7
	v_add_u32_e32 v8, 1, v5
	v_cmp_ge_u32_e32 vcc, v7, v6
	s_nop 1
	v_cndmask_b32_e32 v5, v5, v8, vcc
	v_sub_u32_e32 v8, v7, v6
	v_cndmask_b32_e32 v7, v7, v8, vcc
	v_add_u32_e32 v8, 1, v5
	v_cmp_ge_u32_e32 vcc, v7, v6
	v_add_u32_e32 v7, 1, v9
	s_nop 0
	v_cndmask_b32_e32 v5, v5, v8, vcc
	v_mul_lo_u32 v8, v6, v5
	v_add_u32_e32 v6, v8, v6
	v_cmp_ne_u32_e32 vcc, v7, v6
	s_and_saveexec_b64 s[4:5], vcc
	s_xor_b64 s[4:5], exec, s[4:5]
	s_cbranch_execz .LBB0_267
	v_readlane_b32 s24, v249, 49
	v_readlane_b32 s25, v249, 50
	s_waitcnt lgkmcnt(0)
	s_nop 3
	global_load_dword v4, v137, s[24:25] sc1
	s_waitcnt vmcnt(0)
	v_cmp_eq_u32_e32 vcc, v4, v5
	s_and_saveexec_b64 s[24:25], vcc
	s_cbranch_execz .LBB0_266
	s_mov_b32 s28, 1
	s_mov_b64 s[26:27], 0
	s_branch .LBB0_257
